# combination + F1 epilogue: zeroing of the conv history registers moved out of line onto the path that skips the LDS reads (4 sites)
# speedup vs baseline: 1.0058x; 1.0007x over previous
; #define PG8_LAS __attribute__((address_space(3)))
;     __device__ __forceinline__ void operator()(f32x4 (&acc)[2][2][4][2], const Unit& u, int p, int wr, int wc, int fr, int fq) const {
;     ...
;                     f32x4 h62 = (f32x4){0.f, 0.f, 0.f, 0.f}, h63 = h62;
;                     if (g > 0) { h62 = *(const PG8_LAS f32x4*)(X + (((g - 1) * 2 + 0) * 256) + bj * 128 + tcol + 4 * n); h63 = *(const PG8_LAS f32x4*)(X + (((g - 1) * 2 + 1) * 256) + bj * 128 + tcol + 4 * n); }
.Lzd_0:
	v_mov_b32_e32 v90, 0
	v_mov_b32_e32 v91, 0
	v_mov_b32_e32 v92, 0
	v_mov_b32_e32 v93, 0
	v_mov_b32_e32 v106, 0
	v_mov_b32_e32 v107, 0
	v_mov_b32_e32 v108, 0
	v_mov_b32_e32 v109, 0
	s_branch .LBB0_1337
.Lzd_1:
	v_mov_b32_e32 v134, 0
	v_mov_b32_e32 v135, 0
	v_mov_b32_e32 v136, 0
	v_mov_b32_e32 v137, 0
	v_mov_b32_e32 v138, 0
	v_mov_b32_e32 v139, 0
	v_mov_b32_e32 v140, 0
	v_mov_b32_e32 v141, 0
	s_branch .LBB0_1341
.Lzd_2:
	v_mov_b32_e32 v104, 0
	v_mov_b32_e32 v105, 0
	v_mov_b32_e32 v106, 0
	v_mov_b32_e32 v107, 0
	v_mov_b32_e32 v108, 0
	v_mov_b32_e32 v109, 0
	v_mov_b32_e32 v110, 0
	v_mov_b32_e32 v111, 0
	s_branch .LBB0_1345
.Lzd_3:
	v_mov_b32_e32 v62, 0
	v_mov_b32_e32 v63, 0
	v_mov_b32_e32 v64, 0
	v_mov_b32_e32 v65, 0
	v_mov_b32_e32 v98, 0
	v_mov_b32_e32 v99, 0
	v_mov_b32_e32 v100, 0
	v_mov_b32_e32 v101, 0
	s_branch .LBB0_1349

; #define PG8_LAS __attribute__((address_space(3)))
;     __device__ __forceinline__ void operator()(f32x4 (&acc)[2][2][4][2], const Unit& u, int p, int wr, int wc, int fr, int fq) const {
;     ...
;         asm volatile("s_waitcnt lgkmcnt(0)" ::: "memory"); __builtin_amdgcn_s_barrier(); asm volatile("" ::: "memory");
;         const PG8_LAS float* Tw = TW + p * 1024 + tcol;
;         const int row0 = u.pm * BM + wr * 64 + 4 * fr;
; #pragma unroll
;         for (int ai = 0; ai < 2; ++ai) { const int g = ai * 2 + wr;
; #pragma unroll
;             for (int bj = 0; bj < 2; ++bj)
; #pragma unroll
;                 for (int n = 0; n < 2; ++n) {
;                     const f32x4 w0 = *(const PG8_LAS f32x4*)(Tw + bj * 128 + 4 * n), w1 = *(const PG8_LAS f32x4*)(Tw + 256 + bj * 128 + 4 * n), w2 = *(const PG8_LAS f32x4*)(Tw + 512 + bj * 128 + 4 * n), bb = *(const PG8_LAS f32x4*)(Tw + 768 + bj * 128 + 4 * n);
;                     f32x4 h62 = (f32x4){0.f, 0.f, 0.f, 0.f}, h63 = h62;
;                     if (g > 0) { h62 = *(const PG8_LAS f32x4*)(X + (((g - 1) * 2 + 0) * 256) + bj * 128 + tcol + 4 * n); h63 = *(const PG8_LAS f32x4*)(X + (((g - 1) * 2 + 1) * 256) + bj * 128 + tcol + 4 * n); }
.LBB0_1335:
	s_or_b64 exec, exec, s[12:13]
	s_lshl_b32 s0, s0, 12
	s_waitcnt lgkmcnt(0)
	s_barrier
	v_add_u32_e32 v220, s0, v209
	ds_read_b128 v[86:89], v220
	ds_read_b128 v[170:173], v220 offset:1024
	ds_read_b128 v[174:177], v220 offset:2048
	ds_read_b128 v[178:181], v220 offset:3072
	v_cndmask_b32_e64 v90, 0, 1, s[80:81]
	v_mov_b32_e32 v94, 0
	v_cmp_ne_u32_e64 s[12:13], 1, v90
	s_andn2_b64 vcc, exec, s[80:81]
	s_cbranch_vccnz .Lzd_0
	ds_read_b128 v[106:109], v212
	ds_read_b128 v[90:93], v211

; #define PG8_LAS __attribute__((address_space(3)))
; template <int SH> __device__ __forceinline__ float dpp_shr_fill(float fill, float cur) { return i2f(__builtin_amdgcn_update_dpp(f2i(fill), f2i(cur), 0x110 + SH, 0xf, 0xf, false)); }
;     __device__ __forceinline__ void operator()(f32x4 (&acc)[2][2][4][2], const Unit& u, int p, int wr, int wc, int fr, int fq) const {
;     ...
;                 for (int n = 0; n < 2; ++n) {
;                     const f32x4 w0 = *(const PG8_LAS f32x4*)(Tw + bj * 128 + 4 * n), w1 = *(const PG8_LAS f32x4*)(Tw + 256 + bj * 128 + 4 * n), w2 = *(const PG8_LAS f32x4*)(Tw + 512 + bj * 128 + 4 * n), bb = *(const PG8_LAS f32x4*)(Tw + 768 + bj * 128 + 4 * n);
;                     f32x4 h62 = (f32x4){0.f, 0.f, 0.f, 0.f}, h63 = h62;
;                     if (g > 0) { h62 = *(const PG8_LAS f32x4*)(X + (((g - 1) * 2 + 0) * 256) + bj * 128 + tcol + 4 * n); h63 = *(const PG8_LAS f32x4*)(X + (((g - 1) * 2 + 1) * 256) + bj * 128 + tcol + 4 * n); }
;                     const f32x4 x0 = acc[ai][bj][0][n], x1 = acc[ai][bj][1][n], x2 = acc[ai][bj][2][n], x3 = acc[ai][bj][3][n];
;                     f32x4 s2, s3;
; #pragma unroll
;                     for (int e = 0; e < 4; ++e) { s3[e] = dpp_shr_fill<1>(h63[e], x3[e]); s2[e] = dpp_shr_fill<1>(h62[e], x2[e]); }
;                     f32x4 r0 = bb + w2 * x0 + w1 * s3 + w0 * s2, r1 = bb + w2 * x1 + w1 * x0 + w0 * s3, r2 = bb + w2 * x2 + w1 * x1 + w0 * x0, r3 = bb + w2 * x3 + w1 * x2 + w0 * x1;
;                     asm volatile("" : "+v"(r0), "+v"(r1), "+v"(r2), "+v"(r3));
;                     acc[ai][bj][0][n] = r0; acc[ai][bj][1][n] = r1; acc[ai][bj][2][n] = r2; acc[ai][bj][3][n] = r3;
.LBB0_1339:
	s_waitcnt lgkmcnt(0)
	s_nop 0
	v_mov_b32_dpp v142, v134 row_shr:1 row_mask:0xf bank_mask:0xf
	v_mov_b32_dpp v143, v135 row_shr:1 row_mask:0xf bank_mask:0xf
	v_mov_b32_dpp v144, v136 row_shr:1 row_mask:0xf bank_mask:0xf
	v_mov_b32_dpp v145, v137 row_shr:1 row_mask:0xf bank_mask:0xf
	v_pk_fma_f32 v[146:147], v[112:113], v[172:173], v[176:177]
	v_pk_fma_f32 v[148:149], v[110:111], v[170:171], v[174:175]
	v_mov_b32_dpp v94, v138 row_shr:1 row_mask:0xf bank_mask:0xf
	v_mov_b32_dpp v95, v139 row_shr:1 row_mask:0xf bank_mask:0xf
	v_mov_b32_dpp v96, v140 row_shr:1 row_mask:0xf bank_mask:0xf
	v_mov_b32_dpp v97, v141 row_shr:1 row_mask:0xf bank_mask:0xf
	v_pk_fma_f32 v[178:179], v[166:167], v[142:143], v[148:149]
	v_pk_fma_f32 v[146:147], v[168:169], v[144:145], v[146:147]
	s_nop 0
	v_pk_fma_f32 v[148:149], v[164:165], v[96:97], v[146:147]
	v_pk_fma_f32 v[146:147], v[162:163], v[94:95], v[178:179]
	v_pk_fma_f32 v[94:95], v[160:161], v[172:173], v[176:177]
	v_pk_fma_f32 v[96:97], v[158:159], v[170:171], v[174:175]
	v_pk_fma_f32 v[94:95], v[112:113], v[168:169], v[94:95]
	v_pk_fma_f32 v[96:97], v[110:111], v[166:167], v[96:97]
	v_pk_fma_f32 v[144:145], v[164:165], v[144:145], v[94:95]
	v_pk_fma_f32 v[142:143], v[162:163], v[142:143], v[96:97]
	v_pk_fma_f32 v[94:95], v[140:141], v[172:173], v[176:177]
	v_pk_fma_f32 v[96:97], v[138:139], v[170:171], v[174:175]
	v_pk_fma_f32 v[94:95], v[160:161], v[168:169], v[94:95]
	v_pk_fma_f32 v[96:97], v[158:159], v[166:167], v[96:97]
	v_pk_fma_f32 v[112:113], v[112:113], v[164:165], v[94:95]
	v_pk_fma_f32 v[110:111], v[110:111], v[162:163], v[96:97]
	v_pk_fma_f32 v[94:95], v[136:137], v[172:173], v[176:177]
	v_pk_fma_f32 v[96:97], v[134:135], v[170:171], v[174:175]
	v_pk_fma_f32 v[94:95], v[140:141], v[168:169], v[94:95]
	v_pk_fma_f32 v[134:135], v[138:139], v[166:167], v[96:97]
	v_pk_fma_f32 v[96:97], v[160:161], v[164:165], v[94:95]
	v_pk_fma_f32 v[94:95], v[158:159], v[162:163], v[134:135]
	s_nop 0
	ds_read_b128 v[166:169], v220 offset:512
	ds_read_b128 v[170:173], v220 offset:1536
	ds_read_b128 v[174:177], v220 offset:2560
	ds_read_b128 v[178:181], v220 offset:3584
	v_mov_b32_e32 v158, 0
	s_and_b64 vcc, exec, s[12:13]
	s_cbranch_vccnz .Lzd_1
	ds_read_b128 v[138:141], v216
	ds_read_b128 v[134:137], v215

; __device__ __forceinline__ unsigned cvt_pk_bf16(float lo, float hi) { unsigned r; asm volatile("v_cvt_pk_bf16_f32 %0, %1, %2" : "=v"(r) : "v"(lo), "v"(hi)); return r; }
; #define EPI_ST16(p, v) __builtin_nontemporal_store((v), (u32x4*)(p))
; template <int SH> __device__ __forceinline__ float dpp_shr_fill(float fill, float cur) { return i2f(__builtin_amdgcn_update_dpp(f2i(fill), f2i(cur), 0x110 + SH, 0xf, 0xf, false)); }
; #define ACT(t) (!SK || KBASE(t) <= qlo + QBLK - 1)
;     __device__ __forceinline__ void operator()(f32x4 (&acc)[2][2][4][2], const Unit& u, int p, int wr, int wc, int fr, int fq) const {
;     ...
;                     const f32x4 x0 = acc[ai][bj][0][n], x1 = acc[ai][bj][1][n], x2 = acc[ai][bj][2][n], x3 = acc[ai][bj][3][n];
;                     f32x4 s2, s3;
; #pragma unroll
;                     for (int e = 0; e < 4; ++e) { s3[e] = dpp_shr_fill<1>(h63[e], x3[e]); s2[e] = dpp_shr_fill<1>(h62[e], x2[e]); }
;                     f32x4 r0 = bb + w2 * x0 + w1 * s3 + w0 * s2, r1 = bb + w2 * x1 + w1 * x0 + w0 * s3, r2 = bb + w2 * x2 + w1 * x1 + w0 * x0, r3 = bb + w2 * x3 + w1 * x2 + w0 * x1;
;                     asm volatile("" : "+v"(r0), "+v"(r1), "+v"(r2), "+v"(r3));
;                     acc[ai][bj][0][n] = r0; acc[ai][bj][1][n] = r1; acc[ai][bj][2][n] = r2; acc[ai][bj][3][n] = r3;
;                     __builtin_amdgcn_sched_barrier(0); }
; #pragma unroll
;             for (int m = 0; m < 4; ++m) { f32x4 o[2];
; #pragma unroll
;                 for (int n = 0; n < 2; ++n) { const f32x4 gt = acc[ai][0][m][n], a = gt * -1.4426950408889634f, gu = gt * acc[ai][1][m][n];
;                     f32x4 ex; ex.x = __builtin_amdgcn_exp2f(a.x); ex.y = __builtin_amdgcn_exp2f(a.y); ex.z = __builtin_amdgcn_exp2f(a.z); ex.w = __builtin_amdgcn_exp2f(a.w);
;                     const f32x4 d = ex + 1.0f; f32x4 r; r.x = __builtin_amdgcn_rcpf(d.x); r.y = __builtin_amdgcn_rcpf(d.y); r.z = __builtin_amdgcn_rcpf(d.z); r.w = __builtin_amdgcn_rcpf(d.w);
;                     o[n] = gu * r; }
;                 u32x4 w; w.x = cvt_pk_bf16(o[0][0], o[0][1]); w.y = cvt_pk_bf16(o[0][2], o[0][3]); w.z = cvt_pk_bf16(o[1][0], o[1][1]); w.w = cvt_pk_bf16(o[1][2], o[1][3]);
;                 EPI_ST16(ACT + (size_t)(row0 + ai * HALF + m) * 5504 + ch0, w); }
.LBB0_1343:
	s_waitcnt lgkmcnt(0)
	s_nop 0
	v_mov_b32_dpp v170, v118 row_shr:1 row_mask:0xf bank_mask:0xf
	v_mov_b32_dpp v171, v119 row_shr:1 row_mask:0xf bank_mask:0xf
	v_mov_b32_dpp v172, v120 row_shr:1 row_mask:0xf bank_mask:0xf
	v_mov_b32_dpp v173, v121 row_shr:1 row_mask:0xf bank_mask:0xf
	v_pk_fma_f32 v[176:177], v[104:105], v[156:157], v[168:169]
	v_pk_fma_f32 v[178:179], v[102:103], v[154:155], v[166:167]
	v_mov_b32_dpp v158, v122 row_shr:1 row_mask:0xf bank_mask:0xf
	v_mov_b32_dpp v159, v123 row_shr:1 row_mask:0xf bank_mask:0xf
	v_mov_b32_dpp v160, v124 row_shr:1 row_mask:0xf bank_mask:0xf
	v_mov_b32_dpp v161, v125 row_shr:1 row_mask:0xf bank_mask:0xf
	v_pk_fma_f32 v[178:179], v[150:151], v[170:171], v[178:179]
	v_pk_fma_f32 v[176:177], v[152:153], v[172:173], v[176:177]
	v_pk_fma_f32 v[158:159], v[130:131], v[158:159], v[178:179]
	v_pk_fma_f32 v[160:161], v[132:133], v[160:161], v[176:177]
	v_pk_fma_f32 v[176:177], v[100:101], v[156:157], v[168:169]
	v_pk_fma_f32 v[178:179], v[98:99], v[154:155], v[166:167]
	v_pk_fma_f32 v[176:177], v[104:105], v[152:153], v[176:177]
	v_pk_fma_f32 v[178:179], v[102:103], v[150:151], v[178:179]
	v_pk_fma_f32 v[172:173], v[132:133], v[172:173], v[176:177]
	v_pk_fma_f32 v[170:171], v[130:131], v[170:171], v[178:179]
	v_pk_fma_f32 v[176:177], v[124:125], v[156:157], v[168:169]
	v_pk_fma_f32 v[178:179], v[122:123], v[154:155], v[166:167]
	v_pk_fma_f32 v[120:121], v[120:121], v[156:157], v[168:169]
	v_pk_fma_f32 v[118:119], v[118:119], v[154:155], v[166:167]
	v_pk_fma_f32 v[176:177], v[100:101], v[152:153], v[176:177]
	v_pk_fma_f32 v[178:179], v[98:99], v[150:151], v[178:179]
	v_pk_fma_f32 v[120:121], v[124:125], v[152:153], v[120:121]
	v_pk_fma_f32 v[118:119], v[122:123], v[150:151], v[118:119]
	v_lshl_add_u32 v174, s94, 8, v207
	v_pk_fma_f32 v[104:105], v[104:105], v[132:133], v[176:177]
	v_pk_fma_f32 v[102:103], v[102:103], v[130:131], v[178:179]
	v_pk_fma_f32 v[100:101], v[100:101], v[132:133], v[120:121]
	v_pk_fma_f32 v[98:99], v[98:99], v[130:131], v[118:119]
	s_nop 0
	v_pk_mul_f32 v[118:119], v[116:117], s[42:43] op_sel_hi:[1,0]
	v_pk_mul_f32 v[120:121], v[114:115], s[42:43] op_sel_hi:[1,0]
	v_exp_f32_e32 v118, v118
	v_exp_f32_e32 v120, v120
	v_exp_f32_e32 v119, v119
	v_exp_f32_e32 v121, v121
	v_pk_mul_f32 v[122:123], v[148:149], s[42:43] op_sel_hi:[1,0]
	v_pk_mul_f32 v[124:125], v[146:147], s[42:43] op_sel_hi:[1,0]
	v_pk_add_f32 v[118:119], v[118:119], 1.0 op_sel_hi:[1,0]
	v_pk_add_f32 v[120:121], v[120:121], 1.0 op_sel_hi:[1,0]
	v_rcp_f32_e32 v118, v118
	v_rcp_f32_e32 v120, v120
	v_rcp_f32_e32 v121, v121
	v_rcp_f32_e32 v119, v119
	v_exp_f32_e32 v124, v124
	v_exp_f32_e32 v122, v122
	v_exp_f32_e32 v123, v123
	v_exp_f32_e32 v125, v125
	v_pk_mul_f32 v[116:117], v[116:117], v[164:165]
	v_pk_mul_f32 v[114:115], v[114:115], v[162:163]
	v_pk_mul_f32 v[116:117], v[118:119], v[116:117]
	v_pk_mul_f32 v[114:115], v[120:121], v[114:115]
	v_pk_add_f32 v[118:119], v[122:123], 1.0 op_sel_hi:[1,0]
	v_pk_add_f32 v[120:121], v[124:125], 1.0 op_sel_hi:[1,0]
	v_rcp_f32_e32 v118, v118
	v_rcp_f32_e32 v120, v120
	v_rcp_f32_e32 v119, v119
	v_rcp_f32_e32 v121, v121
	v_pk_mul_f32 v[122:123], v[148:149], v[160:161]
	v_pk_mul_f32 v[124:125], v[146:147], v[158:159]
	v_pk_mul_f32 v[122:123], v[118:119], v[122:123]
	v_pk_mul_f32 v[120:121], v[120:121], v[124:125]
	v_cvt_pk_bf16_f32 v118, v114, v115
	v_cvt_pk_bf16_f32 v119, v116, v117
	v_mov_b64_e32 v[116:117], s[76:77]
	v_cvt_pk_bf16_f32 v120, v120, v121
	v_cvt_pk_bf16_f32 v121, v122, v123
	v_mad_i64_i32 v[122:123], s[12:13], v174, s22, v[116:117]
	v_lshlrev_b64 v[114:115], 1, v[200:201]
	v_lshl_add_u64 v[122:123], v[122:123], 0, v[114:115]
	global_store_dwordx4 v[122:123], v[118:121], off
	v_pk_mul_f32 v[122:123], v[144:145], s[42:43] op_sel_hi:[1,0]
	v_pk_mul_f32 v[124:125], v[142:143], s[42:43] op_sel_hi:[1,0]
	v_pk_mul_f32 v[118:119], v[108:109], s[42:43] op_sel_hi:[1,0]
	v_pk_mul_f32 v[120:121], v[106:107], s[42:43] op_sel_hi:[1,0]
	v_exp_f32_e32 v118, v118
	v_exp_f32_e32 v119, v119
	v_exp_f32_e32 v120, v120
	v_exp_f32_e32 v121, v121
	v_exp_f32_e32 v122, v122
	v_pk_add_f32 v[118:119], v[118:119], 1.0 op_sel_hi:[1,0]
	v_exp_f32_e32 v123, v123
	v_pk_add_f32 v[120:121], v[120:121], 1.0 op_sel_hi:[1,0]
	v_rcp_f32_e32 v118, v118
	v_rcp_f32_e32 v119, v119
	v_rcp_f32_e32 v120, v120
	v_rcp_f32_e32 v121, v121
	v_exp_f32_e32 v124, v124
	v_exp_f32_e32 v125, v125
	v_pk_mul_f32 v[108:109], v[108:109], v[140:141]
; #define PG8_LAS __attribute__((address_space(3)))
;     __device__ __forceinline__ void operator()(f32x4 (&acc)[2][2][4][2], const Unit& u, int p, int wr, int wc, int fr, int fq) const {
;     ...
;         for (int ai = 0; ai < 2; ++ai) { const int g = ai * 2 + wr;
; #pragma unroll
;             for (int bj = 0; bj < 2; ++bj)
; #pragma unroll
;                 for (int n = 0; n < 2; ++n) {
;                     const f32x4 w0 = *(const PG8_LAS f32x4*)(Tw + bj * 128 + 4 * n), w1 = *(const PG8_LAS f32x4*)(Tw + 256 + bj * 128 + 4 * n), w2 = *(const PG8_LAS f32x4*)(Tw + 512 + bj * 128 + 4 * n), bb = *(const PG8_LAS f32x4*)(Tw + 768 + bj * 128 + 4 * n);
;                     f32x4 h62 = (f32x4){0.f, 0.f, 0.f, 0.f}, h63 = h62;
;                     if (g > 0) { h62 = *(const PG8_LAS f32x4*)(X + (((g - 1) * 2 + 0) * 256) + bj * 128 + tcol + 4 * n); h63 = *(const PG8_LAS f32x4*)(X + (((g - 1) * 2 + 1) * 256) + bj * 128 + tcol + 4 * n); }
;                     const f32x4 x0 = acc[ai][bj][0][n], x1 = acc[ai][bj][1][n], x2 = acc[ai][bj][2][n], x3 = acc[ai][bj][3][n];
;                     f32x4 s2, s3;
; #pragma unroll
;                     for (int e = 0; e < 4; ++e) { s3[e] = dpp_shr_fill<1>(h63[e], x3[e]); s2[e] = dpp_shr_fill<1>(h62[e], x2[e]); }
;                     f32x4 r0 = bb + w2 * x0 + w1 * s3 + w0 * s2, r1 = bb + w2 * x1 + w1 * x0 + w0 * s3, r2 = bb + w2 * x2 + w1 * x1 + w0 * x0, r3 = bb + w2 * x3 + w1 * x2 + w0 * x1;
;                     asm volatile("" : "+v"(r0), "+v"(r1), "+v"(r2), "+v"(r3));
;                     acc[ai][bj][0][n] = r0; acc[ai][bj][1][n] = r1; acc[ai][bj][2][n] = r2; acc[ai][bj][3][n] = r3;
;                     __builtin_amdgcn_sched_barrier(0); }
; #pragma unroll
;             for (int m = 0; m < 4; ++m) { f32x4 o[2];
; #pragma unroll
;                 for (int n = 0; n < 2; ++n) { const f32x4 gt = acc[ai][0][m][n], a = gt * -1.4426950408889634f, gu = gt * acc[ai][1][m][n];
;                     f32x4 ex; ex.x = __builtin_amdgcn_exp2f(a.x); ex.y = __builtin_amdgcn_exp2f(a.y); ex.z = __builtin_amdgcn_exp2f(a.z); ex.w = __builtin_amdgcn_exp2f(a.w);
;                     const f32x4 d = ex + 1.0f; f32x4 r; r.x = __builtin_amdgcn_rcpf(d.x); r.y = __builtin_amdgcn_rcpf(d.y); r.z = __builtin_amdgcn_rcpf(d.z); r.w = __builtin_amdgcn_rcpf(d.w);
;                     o[n] = gu * r; }
	v_pk_mul_f32 v[106:107], v[106:107], v[138:139]
	v_pk_mul_f32 v[108:109], v[118:119], v[108:109]
	v_pk_add_f32 v[118:119], v[122:123], 1.0 op_sel_hi:[1,0]
	v_pk_mul_f32 v[106:107], v[120:121], v[106:107]
	v_pk_add_f32 v[120:121], v[124:125], 1.0 op_sel_hi:[1,0]
	v_rcp_f32_e32 v118, v118
	v_rcp_f32_e32 v119, v119
	v_rcp_f32_e32 v120, v120
	v_rcp_f32_e32 v121, v121
	v_pk_mul_f32 v[122:123], v[144:145], v[172:173]
	v_pk_mul_f32 v[124:125], v[142:143], v[170:171]
	v_pk_mul_f32 v[118:119], v[118:119], v[122:123]
	v_pk_mul_f32 v[120:121], v[120:121], v[124:125]
	v_cvt_pk_bf16_f32 v106, v106, v107
	v_cvt_pk_bf16_f32 v107, v108, v109
	v_pk_mul_f32 v[102:103], v[110:111], v[102:103]
	v_cvt_pk_bf16_f32 v108, v120, v121
	v_cvt_pk_bf16_f32 v109, v118, v119
	v_or_b32_e32 v118, 1, v174
	v_mad_i64_i32 v[118:119], s[12:13], v118, s22, v[116:117]
	v_lshl_add_u64 v[118:119], v[118:119], 0, v[114:115]
	global_store_dwordx4 v[118:119], v[106:109], off
	v_pk_mul_f32 v[120:121], v[110:111], s[42:43] op_sel_hi:[1,0]
	v_pk_mul_f32 v[118:119], v[112:113], s[42:43] op_sel_hi:[1,0]
	v_pk_mul_f32 v[108:109], v[90:91], s[42:43] op_sel_hi:[1,0]
	v_pk_mul_f32 v[106:107], v[92:93], s[42:43] op_sel_hi:[1,0]
	v_exp_f32_e32 v108, v108
	v_exp_f32_e32 v109, v109
	v_exp_f32_e32 v106, v106
	v_exp_f32_e32 v107, v107
	v_exp_f32_e32 v120, v120
	v_pk_add_f32 v[108:109], v[108:109], 1.0 op_sel_hi:[1,0]
	v_exp_f32_e32 v121, v121
	v_rcp_f32_e32 v108, v108
	v_rcp_f32_e32 v109, v109
	v_pk_mul_f32 v[90:91], v[90:91], v[134:135]
	v_pk_add_f32 v[106:107], v[106:107], 1.0 op_sel_hi:[1,0]
	v_exp_f32_e32 v118, v118
	v_rcp_f32_e32 v106, v106
	v_rcp_f32_e32 v107, v107
	v_exp_f32_e32 v119, v119
	v_pk_mul_f32 v[90:91], v[108:109], v[90:91]
	v_pk_add_f32 v[108:109], v[120:121], 1.0 op_sel_hi:[1,0]
	v_pk_mul_f32 v[92:93], v[92:93], v[136:137]
	v_rcp_f32_e32 v108, v108
	v_rcp_f32_e32 v109, v109
	v_pk_mul_f32 v[92:93], v[106:107], v[92:93]
	v_pk_add_f32 v[106:107], v[118:119], 1.0 op_sel_hi:[1,0]
	v_cvt_pk_bf16_f32 v90, v90, v91
	v_pk_mul_f32 v[102:103], v[108:109], v[102:103]
	v_rcp_f32_e32 v106, v106
	v_rcp_f32_e32 v107, v107
	v_cvt_pk_bf16_f32 v91, v92, v93
	v_cvt_pk_bf16_f32 v92, v102, v103
	v_or_b32_e32 v102, 2, v174
	v_mad_i64_i32 v[102:103], s[12:13], v102, s22, v[116:117]
	v_pk_mul_f32 v[104:105], v[112:113], v[104:105]
	v_lshl_add_u64 v[102:103], v[102:103], 0, v[114:115]
	v_pk_mul_f32 v[104:105], v[106:107], v[104:105]
	s_nop 0
	v_cvt_pk_bf16_f32 v93, v104, v105
	global_store_dwordx4 v[102:103], v[90:93], off
	v_pk_mul_f32 v[102:103], v[96:97], s[42:43] op_sel_hi:[1,0]
	v_pk_mul_f32 v[104:105], v[94:95], s[42:43] op_sel_hi:[1,0]
	v_pk_mul_f32 v[90:91], v[88:89], s[42:43] op_sel_hi:[1,0]
	v_pk_mul_f32 v[92:93], v[86:87], s[42:43] op_sel_hi:[1,0]
	v_exp_f32_e32 v90, v90
	v_exp_f32_e32 v91, v91
	v_exp_f32_e32 v92, v92
	v_exp_f32_e32 v93, v93
	v_exp_f32_e32 v102, v102
	v_pk_add_f32 v[90:91], v[90:91], 1.0 op_sel_hi:[1,0]
	v_exp_f32_e32 v103, v103
	v_pk_add_f32 v[92:93], v[92:93], 1.0 op_sel_hi:[1,0]
	v_rcp_f32_e32 v90, v90
	v_rcp_f32_e32 v91, v91
	v_rcp_f32_e32 v92, v92
	v_rcp_f32_e32 v93, v93
	v_exp_f32_e32 v104, v104
	v_exp_f32_e32 v105, v105
	v_pk_mul_f32 v[88:89], v[88:89], v[128:129]
	v_pk_mul_f32 v[86:87], v[86:87], v[126:127]
	v_pk_mul_f32 v[88:89], v[90:91], v[88:89]
	v_pk_add_f32 v[90:91], v[102:103], 1.0 op_sel_hi:[1,0]
	v_pk_mul_f32 v[86:87], v[92:93], v[86:87]
	v_pk_add_f32 v[92:93], v[104:105], 1.0 op_sel_hi:[1,0]
	v_rcp_f32_e32 v90, v90
	v_rcp_f32_e32 v91, v91
	v_rcp_f32_e32 v92, v92
	v_rcp_f32_e32 v93, v93
	v_pk_mul_f32 v[96:97], v[96:97], v[100:101]
	v_pk_mul_f32 v[94:95], v[94:95], v[98:99]
	v_pk_mul_f32 v[90:91], v[90:91], v[96:97]
	v_pk_mul_f32 v[92:93], v[92:93], v[94:95]
	v_cvt_pk_bf16_f32 v86, v86, v87
	v_cvt_pk_bf16_f32 v87, v88, v89
	s_nop 0
	v_cvt_pk_bf16_f32 v88, v92, v93
	v_cvt_pk_bf16_f32 v89, v90, v91
	v_or_b32_e32 v90, 3, v174
	v_mad_i64_i32 v[90:91], s[12:13], v90, s22, v[116:117]
	v_lshl_add_u64 v[90:91], v[90:91], 0, v[114:115]
	global_store_dwordx4 v[90:91], v[86:89], off
	ds_read_b128 v[88:91], v220
	ds_read_b128 v[92:95], v220 offset:1024
	ds_read_b128 v[96:99], v220 offset:2048
	ds_read_b128 v[100:103], v220 offset:3072
	v_cndmask_b32_e64 v87, 0, 1, s[82:83]
	v_mov_b32_e32 v86, 0
	v_cmp_ne_u32_e64 s[12:13], 1, v87
	s_andn2_b64 vcc, exec, s[82:83]
	s_cbranch_vccnz .Lzd_2
	ds_read_b128 v[108:111], v210 offset:2048
	ds_read_b128 v[104:107], v210 offset:3072

; #define PG8_LAS __attribute__((address_space(3)))
; template <int SH> __device__ __forceinline__ float dpp_shr_fill(float fill, float cur) { return i2f(__builtin_amdgcn_update_dpp(f2i(fill), f2i(cur), 0x110 + SH, 0xf, 0xf, false)); }
;     template <bool PR = false> __device__ __forceinline__ void apply(f32x4 (&acc)[2][2][4][2], int p, int wr, int wc, int fr, int fq) const {
;     ...
;             for (int m = 0; m < 4; ++m) rs[ai][m] = __builtin_amdgcn_rsqf((float)Tr[ai * HALF + (PR ? m : m * 16)] * (1.0f / (1048576.0f * 2048.0f)) + 1e-6f);
; #pragma unroll
;         for (int bj = 0; bj < 2; ++bj)
; #pragma unroll
;             for (int n = 0; n < 2; ++n) { const f32x4 bv = *(const PG8_LAS f32x4*)(Tb + bj * HALF + 4 * n);
; #pragma unroll
;                 for (int ai = 0; ai < 2; ++ai)
; #pragma unroll
;                     for (int m = 0; m < 4; ++m) acc[ai][bj][m][n] = acc[ai][bj][m][n] * rs[ai][m] + bv; }
;     __device__ __forceinline__ void operator()(f32x4 (&acc)[2][2][4][2], const Unit& u, int p, int wr, int wc, int fr, int fq) const {
;     ...
;                     const f32x4 w0 = *(const PG8_LAS f32x4*)(Tw + bj * 128 + 4 * n), w1 = *(const PG8_LAS f32x4*)(Tw + 256 + bj * 128 + 4 * n), w2 = *(const PG8_LAS f32x4*)(Tw + 512 + bj * 128 + 4 * n), bb = *(const PG8_LAS f32x4*)(Tw + 768 + bj * 128 + 4 * n);
;                     f32x4 h62 = (f32x4){0.f, 0.f, 0.f, 0.f}, h63 = h62;
;                     if (g > 0) { h62 = *(const PG8_LAS f32x4*)(X + (((g - 1) * 2 + 0) * 256) + bj * 128 + tcol + 4 * n); h63 = *(const PG8_LAS f32x4*)(X + (((g - 1) * 2 + 1) * 256) + bj * 128 + tcol + 4 * n); }
;                     const f32x4 x0 = acc[ai][bj][0][n], x1 = acc[ai][bj][1][n], x2 = acc[ai][bj][2][n], x3 = acc[ai][bj][3][n];
;                     f32x4 s2, s3;
; #pragma unroll
;                     for (int e = 0; e < 4; ++e) { s3[e] = dpp_shr_fill<1>(h63[e], x3[e]); s2[e] = dpp_shr_fill<1>(h62[e], x2[e]); }
;                     f32x4 r0 = bb + w2 * x0 + w1 * s3 + w0 * s2, r1 = bb + w2 * x1 + w1 * x0 + w0 * s3, r2 = bb + w2 * x2 + w1 * x1 + w0 * x0, r3 = bb + w2 * x3 + w1 * x2 + w0 * x1;
;                     asm volatile("" : "+v"(r0), "+v"(r1), "+v"(r2), "+v"(r3));
;                     acc[ai][bj][0][n] = r0; acc[ai][bj][1][n] = r1; acc[ai][bj][2][n] = r2; acc[ai][bj][3][n] = r3;
.LBB0_1347:
	v_mov_b32_e32 v117, v116
	v_mov_b32_e32 v106, v116
	v_mov_b32_e32 v107, v116
	v_mov_b32_e32 v113, v112
	v_pk_fma_f32 v[24:25], v[24:25], v[106:107], v[68:69]
	v_pk_fma_f32 v[22:23], v[22:23], v[116:117], v[66:67]
	v_mov_b32_e32 v108, v112
	v_mov_b32_e32 v109, v112
	v_pk_fma_f32 v[20:21], v[20:21], v[108:109], v[68:69]
	v_pk_fma_f32 v[18:19], v[18:19], v[112:113], v[66:67]
	s_waitcnt lgkmcnt(0)
	v_mov_b32_dpp v102, v62 row_shr:1 row_mask:0xf bank_mask:0xf
	v_mov_b32_dpp v103, v63 row_shr:1 row_mask:0xf bank_mask:0xf
	v_mov_b32_dpp v104, v64 row_shr:1 row_mask:0xf bank_mask:0xf
	v_mov_b32_dpp v105, v65 row_shr:1 row_mask:0xf bank_mask:0xf
	v_pk_fma_f32 v[66:67], v[24:25], v[96:97], v[100:101]
	v_pk_fma_f32 v[68:69], v[22:23], v[94:95], v[98:99]
	v_mov_b32_dpp v86, v58 row_shr:1 row_mask:0xf bank_mask:0xf
	v_mov_b32_dpp v87, v59 row_shr:1 row_mask:0xf bank_mask:0xf
	v_mov_b32_dpp v88, v60 row_shr:1 row_mask:0xf bank_mask:0xf
	v_mov_b32_dpp v89, v61 row_shr:1 row_mask:0xf bank_mask:0xf
	v_pk_fma_f32 v[66:67], v[92:93], v[104:105], v[66:67]
	v_pk_fma_f32 v[68:69], v[90:91], v[102:103], v[68:69]
	v_pk_fma_f32 v[76:77], v[80:81], v[88:89], v[66:67]
	v_pk_fma_f32 v[74:75], v[78:79], v[86:87], v[68:69]
	v_pk_fma_f32 v[66:67], v[20:21], v[96:97], v[100:101]
	v_pk_fma_f32 v[68:69], v[18:19], v[94:95], v[98:99]
	v_pk_fma_f32 v[66:67], v[24:25], v[92:93], v[66:67]
	v_pk_fma_f32 v[86:87], v[22:23], v[90:91], v[68:69]
	v_pk_fma_f32 v[68:69], v[80:81], v[104:105], v[66:67]
	v_pk_fma_f32 v[66:67], v[78:79], v[102:103], v[86:87]
	v_pk_fma_f32 v[86:87], v[60:61], v[96:97], v[100:101]
	v_pk_fma_f32 v[88:89], v[58:59], v[94:95], v[98:99]
	v_pk_fma_f32 v[64:65], v[64:65], v[96:97], v[100:101]
	v_pk_fma_f32 v[62:63], v[62:63], v[94:95], v[98:99]
	v_pk_fma_f32 v[86:87], v[20:21], v[92:93], v[86:87]
	v_pk_fma_f32 v[88:89], v[18:19], v[90:91], v[88:89]
	v_pk_fma_f32 v[60:61], v[60:61], v[92:93], v[64:65]
	v_pk_fma_f32 v[58:59], v[58:59], v[90:91], v[62:63]
	v_pk_fma_f32 v[24:25], v[24:25], v[80:81], v[86:87]
	v_pk_fma_f32 v[22:23], v[22:23], v[78:79], v[88:89]
	v_pk_fma_f32 v[20:21], v[20:21], v[80:81], v[60:61]
	v_pk_fma_f32 v[18:19], v[18:19], v[78:79], v[58:59]
	s_nop 0
	ds_read_b128 v[78:81], v220 offset:512
	ds_read_b128 v[86:89], v220 offset:1536
	ds_read_b128 v[90:93], v220 offset:2560
	ds_read_b128 v[94:97], v220 offset:3584
	v_mov_b32_e32 v58, 0
	s_and_b64 vcc, exec, s[12:13]
	s_cbranch_vccnz .Lzd_3
	ds_read_b128 v[62:65], v210 offset:2560
	ds_read_b128 v[98:101], v210 offset:3584
